# rinv table fill overlapped with the prologue DMA loads (GU, W_in)
# baseline (speedup 1.0000x reference)
; __device__ __forceinline__ float rinv_of(const float* P, int row) {
;     const f32x4* p = (const f32x4*)(P + (size_t)row * 16);
;     const f32x4 a = p[0], b = p[1], c = p[2], d = p[3];
;     const float s = ((a[0] + a[1]) + (a[2] + a[3])) + ((b[0] + b[1]) + (b[2] + b[3])) + ((c[0] + c[1]) + (c[2] + c[3])) + ((d[0] + d[1]) + (d[2] + d[3]));
;     return __builtin_amdgcn_rsqf(s * (1.0f / DM) + NORM_EPS);
; }
; __global__ void __launch_bounds__(512, 2) fwd(Args a) {
;     ...
;               { pg8::Unit u0; S.pm0 = S.next(0, u0) ? u0.pm : -1; int t = threadIdx.x; asm volatile("" : "+v"(t)); if (S.pm0 >= 0 && t < 256) { const float r = epi::rinv_of(P, S.pm0 * 256 + t); RT[t] = r; RT[256 + t] = r; } __syncthreads(); }
.LBB0_163:
	v_mov_b32_e32 v0, v190
	s_cmp_gt_i32 s28, -1
	s_cselect_b64 s[4:5], -1, 0
	v_cmp_gt_i32_e32 vcc, s3, v0
	s_and_b64 s[8:9], s[4:5], vcc
	s_and_saveexec_b64 s[4:5], s[8:9]
	s_branch .LBB0_165
	v_lshl_add_u32 v2, s28, 8, v0
	v_ashrrev_i32_e32 v3, 31, v2
	v_lshlrev_b64 v[2:3], 6, v[2:3]
	v_lshl_add_u64 v[14:15], s[36:37], 0, v[2:3]
	global_load_dwordx4 v[2:5], v[14:15], off
	global_load_dwordx4 v[6:9], v[14:15], off offset:16
	global_load_dwordx4 v[10:13], v[14:15], off offset:32
	s_nop 0
	global_load_dwordx4 v[14:17], v[14:15], off offset:48
	v_lshl_add_u32 v0, v0, 2, 0
	v_add_u32_e32 v0, 0x24900, v0
	s_waitcnt vmcnt(0)
	v_add_f32_e32 v1, v2, v3
	v_add_f32_e32 v2, v4, v5
	s_waitcnt vmcnt(2)
	v_add_f32_e32 v3, v6, v7
	v_add_f32_e32 v4, v8, v9
	s_waitcnt vmcnt(1)
	v_add_f32_e32 v5, v10, v11
	v_add_f32_e32 v6, v12, v13
	v_add_f32_e32 v1, v1, v2
	v_add_f32_e32 v2, v3, v4
	s_waitcnt vmcnt(0)
	v_add_f32_e32 v7, v14, v15
	v_add_f32_e32 v8, v16, v17
	v_add_f32_e32 v3, v5, v6
	v_add_f32_e32 v1, v1, v2
	v_add_f32_e32 v1, v1, v3
	v_add_f32_e32 v2, v7, v8
	v_add_f32_e32 v1, v1, v2
	v_fmamk_f32 v1, v1, 0x3a800000, v195
	v_rsq_f32_e32 v1, v1
	ds_write2st64_b32 v0, v1, v1 offset1:4

; #define PG8_STAGE(bufoff, gbase, voff) do { _Pragma("unroll") for (int _i = 0; _i < 2; ++_i) \
;         __builtin_amdgcn_global_load_lds((const unsigned*)((const char*)(gbase) + (voff)[_i]), (PG8_LAS unsigned*)(lds + (bufoff) + ldsw + _i * 8192), 16, 0, 0); } while (0)
; #define PG8_WAIT_V(n) asm volatile("s_waitcnt vmcnt(" #n ")" ::: "memory")
; #define PG8_BAR __builtin_amdgcn_s_barrier()
; template <class Epi, class Sched, bool ALIGN_EPI = false, bool SP2 = false, bool HALFM = false>
; __device__ __forceinline__ void gemm_phase(PG8_LAS unsigned char* lds, const Gemm g, const Sched& S, const Epi& E) {
;     ...
;         PG8_STAGE(PG8_SB(0, 0), cB, voffB); PG8_STAGE(PG8_SB(0, 1), cB + hstep, voffB); PG8_STAGE(PG8_SA(0, 0), cA, voffA); PG8_STAGE(PG8_SA(0, 1), cA + hstep, voffA);
;         if (wr == 1) PG8_BAR;
;         PG8_WAIT_V(2); PG8_BAR;
;         PG8_STAGE(PG8_SB(1, 0), cB + kstep, voffB); PG8_STAGE(PG8_SA(1, 0), cA + kstep, voffA); PG8_STAGE(PG8_SB(1, 1), cB + hstep + kstep, voffB);
;         PG8_WAIT_V(6); PG8_BAR;
; __device__ __forceinline__ float rinv_of(const float* P, int row) {
;     const f32x4* p = (const f32x4*)(P + (size_t)row * 16);
;     const f32x4 a = p[0], b = p[1], c = p[2], d = p[3];
;     const float s = ((a[0] + a[1]) + (a[2] + a[3])) + ((b[0] + b[1]) + (b[2] + b[3])) + ((c[0] + c[1]) + (c[2] + c[3])) + ((d[0] + d[1]) + (d[2] + d[3]));
;     return __builtin_amdgcn_rsqf(s * (1.0f / DM) + NORM_EPS);
; }
.LBB0_172:
	v_readlane_b32 s22, v254, 5
	s_lshl_b32 s5, s5, 5
	v_mov_b32_e32 v131, v81
	v_readlane_b32 s23, v254, 6
	s_and_b32 s12, s5, 0x60
	s_add_i32 m0, s47, 0x18000
	v_lshl_add_u64 v[0:1], v[0:1], 0, s[82:83]
	v_lshl_add_u64 v[12:13], s[22:23], 0, v[130:131]
	v_mov_b32_e32 v133, v81
	s_lshl_b32 s9, s8, 13
	s_lshl_b32 s5, s12, 7
	global_load_lds_dwordx4 v[0:1], off
	v_lshl_add_u64 v[0:1], v[2:3], 0, s[82:83]
	s_add_i32 m0, s47, 0x1a000
	s_add_i32 s51, s47, 0x8000
	s_add_i32 s52, s47, 0xa000
	v_lshl_add_u64 v[14:15], s[22:23], 0, v[132:133]
	global_load_lds_dwordx4 v[0:1], off
	v_lshl_add_u64 v[0:1], v[12:13], 0, s[82:83]
	s_mov_b32 m0, s51
	s_add_u32 s10, s24, 0x40080
	global_load_lds_dwordx4 v[0:1], off
	v_lshl_add_u64 v[0:1], v[14:15], 0, s[82:83]
	s_mov_b32 m0, s52
	s_addc_u32 s11, s25, 0
	global_load_lds_dwordx4 v[0:1], off
	s_add_i32 m0, s47, 0x1c000
	v_lshl_add_u64 v[0:1], s[10:11], 0, v[80:81]
	global_load_lds_dwordx4 v[0:1], off
	v_lshl_add_u64 v[0:1], s[10:11], 0, v[134:135]
	s_add_i32 m0, s47, 0x1e000
	s_cmpk_lt_u32 s4, 0x100
	global_load_lds_dwordx4 v[0:1], off
	s_cselect_b32 s98, 1, 0
	v_cmp_gt_i32_e32 vcc, s3, v190
	s_cmp_gt_i32 s28, -1
	s_cselect_b64 s[100:101], -1, 0
	s_and_b64 vcc, vcc, s[100:101]
	s_and_saveexec_b64 s[100:101], vcc
	s_cbranch_execz .Lgu_rinv_done
	v_lshl_add_u32 v218, s28, 8, v190
	v_ashrrev_i32_e32 v219, 31, v218
	v_lshlrev_b64 v[218:219], 6, v[218:219]
	v_lshl_add_u64 v[218:219], s[36:37], 0, v[218:219]
	global_load_dwordx4 v[202:205], v[218:219], off
	global_load_dwordx4 v[206:209], v[218:219], off offset:16
	global_load_dwordx4 v[210:213], v[218:219], off offset:32
	global_load_dwordx4 v[214:217], v[218:219], off offset:48
	v_lshl_add_u32 v220, v190, 2, 0
	v_add_u32_e32 v220, 0x24900, v220
	s_waitcnt vmcnt(0)
	v_add_f32_e32 v218, v202, v203
	v_add_f32_e32 v202, v204, v205
	v_add_f32_e32 v203, v206, v207
	v_add_f32_e32 v204, v208, v209
	v_add_f32_e32 v205, v210, v211
	v_add_f32_e32 v206, v212, v213
	v_add_f32_e32 v218, v218, v202
	v_add_f32_e32 v202, v203, v204
	v_add_f32_e32 v207, v214, v215
	v_add_f32_e32 v208, v216, v217
	v_add_f32_e32 v203, v205, v206
	v_add_f32_e32 v218, v218, v202
	v_add_f32_e32 v218, v218, v203
	v_add_f32_e32 v202, v207, v208
	v_add_f32_e32 v218, v218, v202
	v_fmamk_f32 v218, v218, 0x3a800000, v195
	v_rsq_f32_e32 v218, v218
	s_nop 0
	ds_write2st64_b32 v220, v218, v218 offset1:4
.Lgu_rinv_done:
	s_or_b64 exec, exec, s[100:101]
	s_cmp_lg_u32 s98, 0
	s_waitcnt vmcnt(8)
	s_barrier
	v_lshrrev_b32_e32 v1, 1, v4
	v_and_b32_e32 v1, 24, v1
	v_and_b32_e32 v0, 15, v4
	v_lshlrev_b32_e32 v2, 1, v1
	v_lshl_or_b32 v142, s8, 6, v0
	v_lshl_or_b32 v2, v0, 6, v2
	v_lshlrev_b32_e32 v0, 2, v0
	v_and_b32_e32 v3, 32, v0
	v_bitop3_b32 v143, v2, s5, v3 bitop3:0xde
	s_cselect_b64 s[4:5], -1, 0
	s_lshl_b32 s8, s8, 8
	s_add_i32 s8, s8, 0
	s_add_i32 s8, s8, 0x24900
	v_add_u32_e32 v145, s8, v0
	v_lshlrev_b32_e32 v0, 14, v5
	v_and_b32_e32 v0, 0xffff8000, v0
	v_or_b32_e32 v144, s12, v1
	v_lshl_add_u32 v0, v6, 11, v0
	v_and_b32_e32 v1, 1, v5
	v_lshl_or_b32 v0, v1, 6, v0
	v_lshl_add_u32 v136, v7, 1, v0
	v_lshlrev_b32_e32 v0, 14, v8
	v_and_b32_e32 v0, 0xffff8000, v0
	s_waitcnt vmcnt(6)
	v_lshl_add_u32 v0, v9, 11, v0
	v_and_b32_e32 v1, 1, v8
	v_bitop3_b32 v4, v2, s9, v3 bitop3:0xde
	v_lshl_or_b32 v0, v1, 6, v0
	v_readlane_b32 s8, v254, 2
	v_mov_b32_e32 v137, v81
	v_lshl_add_u32 v138, v10, 1, v0
	v_mov_b32_e32 v139, v81
	s_mov_b32 s55, 0
	v_add_u32_e32 v146, 0, v4
	v_readlane_b32 s56, v253, 63
	s_mov_b32 s57, s8
	s_mov_b32 s53, 0
	s_barrier
	v_readlane_b32 s9, v254, 3
	s_branch .LBB0_175

; __device__ __forceinline__ float rinv_of(const float* P, int row) {
;     const f32x4* p = (const f32x4*)(P + (size_t)row * 16);
;     const f32x4 a = p[0], b = p[1], c = p[2], d = p[3];
;     const float s = ((a[0] + a[1]) + (a[2] + a[3])) + ((b[0] + b[1]) + (b[2] + b[3])) + ((c[0] + c[1]) + (c[2] + c[3])) + ((d[0] + d[1]) + (d[2] + d[3]));
;     return __builtin_amdgcn_rsqf(s * (1.0f / DM) + NORM_EPS);
; }
; __global__ void __launch_bounds__(512, 2) fwd(Args a) {
;     ...
;               { pg8::Unit u0; S.pm0 = S.next(0, u0) ? u0.pm : -1; int t = threadIdx.x; asm volatile("" : "+v"(t)); if (S.pm0 >= 0 && t < 256) { const float r = epi::rinv_of(P, S.pm0 * 256 + t); RT[t] = r; RT[256 + t] = r; } __syncthreads(); }
.LBB0_397:
	v_mov_b32_e32 v0, v190
	s_cmp_gt_i32 s45, -1
	s_cselect_b64 s[4:5], -1, 0
	v_cmp_gt_i32_e32 vcc, s3, v0
	s_and_b64 s[6:7], s[4:5], vcc
	s_and_saveexec_b64 s[4:5], s[6:7]
	s_branch .LBB0_399
	v_lshl_add_u32 v2, s45, 8, v0
	v_ashrrev_i32_e32 v3, 31, v2
	v_lshlrev_b64 v[2:3], 6, v[2:3]
	v_lshl_add_u64 v[14:15], s[36:37], 0, v[2:3]
	global_load_dwordx4 v[2:5], v[14:15], off
	global_load_dwordx4 v[6:9], v[14:15], off offset:16
	global_load_dwordx4 v[10:13], v[14:15], off offset:32
	s_nop 0
	global_load_dwordx4 v[14:17], v[14:15], off offset:48
	v_lshl_add_u32 v0, v0, 2, 0
	v_add_u32_e32 v0, 0x24900, v0
	s_waitcnt vmcnt(0) lgkmcnt(0)
	v_add_f32_e32 v1, v2, v3
	v_add_f32_e32 v2, v4, v5
	v_add_f32_e32 v3, v6, v7
	v_add_f32_e32 v4, v8, v9
	v_add_f32_e32 v5, v10, v11
	v_add_f32_e32 v6, v12, v13
	v_add_f32_e32 v1, v1, v2
	v_add_f32_e32 v2, v3, v4
	v_add_f32_e32 v7, v14, v15
	v_add_f32_e32 v8, v16, v17
	v_add_f32_e32 v3, v5, v6
	v_add_f32_e32 v1, v1, v2
	v_add_f32_e32 v1, v1, v3
	v_add_f32_e32 v2, v7, v8
	v_add_f32_e32 v1, v1, v2
	v_fmamk_f32 v1, v1, 0x3a800000, v195
	v_rsq_f32_e32 v1, v1
	ds_write2st64_b32 v0, v1, v1 offset1:4

; #define PG8_STAGE(bufoff, gbase, voff) do { _Pragma("unroll") for (int _i = 0; _i < 2; ++_i) \
;         __builtin_amdgcn_global_load_lds((const unsigned*)((const char*)(gbase) + (voff)[_i]), (PG8_LAS unsigned*)(lds + (bufoff) + ldsw + _i * 8192), 16, 0, 0); } while (0)
; #define PG8_WAIT_V(n) asm volatile("s_waitcnt vmcnt(" #n ")" ::: "memory")
; #define PG8_BAR __builtin_amdgcn_s_barrier()
; template <class Epi, class Sched, bool ALIGN_EPI = false, bool SP2 = false, bool HALFM = false>
; __device__ __forceinline__ void gemm_phase(PG8_LAS unsigned char* lds, const Gemm g, const Sched& S, const Epi& E) {
;     ...
;         PG8_STAGE(PG8_SB(0, 0), cB, voffB); PG8_STAGE(PG8_SB(0, 1), cB + hstep, voffB); PG8_STAGE(PG8_SA(0, 0), cA, voffA); PG8_STAGE(PG8_SA(0, 1), cA + hstep, voffA);
;         if (wr == 1) PG8_BAR;
;         PG8_WAIT_V(2); PG8_BAR;
;         PG8_STAGE(PG8_SB(1, 0), cB + kstep, voffB); PG8_STAGE(PG8_SA(1, 0), cA + kstep, voffA); PG8_STAGE(PG8_SB(1, 1), cB + hstep + kstep, voffB);
;         PG8_WAIT_V(6); PG8_BAR;
; __device__ __forceinline__ float rinv_of(const float* P, int row) {
;     const f32x4* p = (const f32x4*)(P + (size_t)row * 16);
;     const f32x4 a = p[0], b = p[1], c = p[2], d = p[3];
;     const float s = ((a[0] + a[1]) + (a[2] + a[3])) + ((b[0] + b[1]) + (b[2] + b[3])) + ((c[0] + c[1]) + (c[2] + c[3])) + ((d[0] + d[1]) + (d[2] + d[3]));
;     return __builtin_amdgcn_rsqf(s * (1.0f / DM) + NORM_EPS);
; }
.LBB0_406:
	v_and_b32_e32 v11, 15, v4
	v_bfe_u32 v4, v4, 4, 2
	v_lshlrev_b32_e32 v17, 4, v4
	v_readlane_b32 s24, v254, 22
	v_lshl_or_b32 v178, s0, 6, v11
	v_lshl_or_b32 v17, v11, 6, v17
	v_lshlrev_b32_e32 v11, 2, v11
	v_mov_b32_e32 v147, v81
	v_readlane_b32 s25, v254, 23
	s_and_b32 s1, s1, 3
	s_lshl_b32 s5, s0, 13
	v_and_b32_e32 v18, 32, v11
	s_add_i32 m0, s49, 0x18000
	v_lshl_add_u64 v[0:1], v[0:1], 0, s[82:83]
	v_lshl_add_u64 v[12:13], s[24:25], 0, v[146:147]
	v_mov_b32_e32 v149, v81
	v_bitop3_b32 v19, v17, s5, v18 bitop3:0xde
	s_lshl_b32 s5, s1, 12
	global_load_lds_dwordx4 v[0:1], off
	v_lshl_add_u64 v[0:1], v[2:3], 0, s[82:83]
	s_add_i32 m0, s49, 0x1a000
	s_add_i32 s53, s49, 0x8000
	s_add_i32 s54, s49, 0xa000
	v_lshl_add_u64 v[14:15], s[24:25], 0, v[148:149]
	global_load_lds_dwordx4 v[0:1], off
	v_lshl_add_u64 v[0:1], v[12:13], 0, s[82:83]
	s_mov_b32 m0, s53
	s_add_u32 s8, s26, 0x40080
	global_load_lds_dwordx4 v[0:1], off
	v_lshl_add_u64 v[0:1], v[14:15], 0, s[82:83]
	s_mov_b32 m0, s54
	s_addc_u32 s9, s27, 0
	global_load_lds_dwordx4 v[0:1], off
	s_add_i32 m0, s49, 0x1c000
	v_lshl_add_u64 v[0:1], s[8:9], 0, v[80:81]
	global_load_lds_dwordx4 v[0:1], off
	v_lshl_add_u64 v[0:1], s[8:9], 0, v[150:151]
	s_add_i32 m0, s49, 0x1e000
	s_cmpk_lt_u32 s4, 0x100
	global_load_lds_dwordx4 v[0:1], off
	s_cselect_b32 s98, 1, 0
	v_cmp_gt_i32_e32 vcc, s3, v190
	s_cmp_gt_i32 s45, -1
	s_cselect_b64 s[100:101], -1, 0
	s_and_b64 vcc, vcc, s[100:101]
	s_and_saveexec_b64 s[100:101], vcc
	s_cbranch_execz .Lwi_rinv_done
	v_lshl_add_u32 v218, s45, 8, v190
	v_ashrrev_i32_e32 v219, 31, v218
	v_lshlrev_b64 v[218:219], 6, v[218:219]
	v_lshl_add_u64 v[218:219], s[36:37], 0, v[218:219]
	global_load_dwordx4 v[202:205], v[218:219], off
	global_load_dwordx4 v[206:209], v[218:219], off offset:16
	global_load_dwordx4 v[210:213], v[218:219], off offset:32
	global_load_dwordx4 v[214:217], v[218:219], off offset:48
	v_lshl_add_u32 v220, v190, 2, 0
	v_add_u32_e32 v220, 0x24900, v220
	s_waitcnt vmcnt(0)
	v_add_f32_e32 v218, v202, v203
	v_add_f32_e32 v202, v204, v205
	v_add_f32_e32 v203, v206, v207
	v_add_f32_e32 v204, v208, v209
	v_add_f32_e32 v205, v210, v211
	v_add_f32_e32 v206, v212, v213
	v_add_f32_e32 v218, v218, v202
	v_add_f32_e32 v202, v203, v204
	v_add_f32_e32 v207, v214, v215
	v_add_f32_e32 v208, v216, v217
	v_add_f32_e32 v203, v205, v206
	v_add_f32_e32 v218, v218, v202
	v_add_f32_e32 v218, v218, v203
	v_add_f32_e32 v202, v207, v208
	v_add_f32_e32 v218, v218, v202
	v_fmamk_f32 v218, v218, 0x3a800000, v195
	v_rsq_f32_e32 v218, v218
	s_nop 0
	ds_write2st64_b32 v220, v218, v218 offset1:4
.Lwi_rinv_done:
	s_or_b64 exec, exec, s[100:101]
	s_cmp_lg_u32 s98, 0
	s_waitcnt vmcnt(8)
	s_barrier
	v_lshlrev_b32_e32 v0, 14, v5
	v_and_b32_e32 v0, 0xffff8000, v0
	v_lshl_add_u32 v0, v6, 11, v0
	v_and_b32_e32 v1, 1, v5
	s_cselect_b64 s[8:9], -1, 0
	s_bitcmp0_b32 s4, 6
	v_lshl_or_b32 v0, v1, 6, v0
	s_cselect_b64 s[10:11], -1, 0
	s_lshl_b32 s0, s0, 8
	v_lshl_add_u32 v162, v7, 1, v0
	v_lshlrev_b32_e32 v0, 14, v8
	s_add_i32 s0, s0, 0
	v_and_b32_e32 v0, 0xffff8000, v0
	v_lshlrev_b32_e32 v16, 3, v4
	s_waitcnt vmcnt(6)
	v_cmp_eq_u32_e32 vcc, 0, v4
	s_add_i32 s0, s0, 0x24900
	v_lshl_add_u32 v0, v9, 11, v0
	v_and_b32_e32 v1, 1, v8
	v_cndmask_b32_e64 v152, 1.0, -1.0, vcc
	v_lshl_or_b32 v180, s1, 5, v16
	v_add_u32_e32 v181, s0, v11
	v_lshl_or_b32 v0, v1, 6, v0
	v_readlane_b32 s0, v254, 19
	v_bitop3_b32 v179, v17, s5, v18 bitop3:0xde
	s_mov_b32 s57, 0
	v_cmp_gt_u32_e64 s[4:5], 2, v4
	v_mov_b32_e32 v153, v152
	v_mov_b32_e32 v160, v152
	v_mov_b32_e32 v161, v152
	v_mov_b32_e32 v163, v81
	v_lshl_add_u32 v164, v10, 1, v0
	v_mov_b32_e32 v165, v81
	v_add_u32_e32 v182, 0, v19
	v_readlane_b32 s59, v254, 10
	s_mov_b32 s58, s0
	s_mov_b32 s55, 0
	s_barrier
	v_readlane_b32 s1, v254, 20
	s_branch .LBB0_409
